# speedup vs baseline: 1.0045x; 1.0026x over previous
; DEV unsigned pack2h(float a, float b) { unsigned r; asm("v_cvt_pk_bf16_f32 %0, %1, %2" : "=v"(r) : "v"(a), "v"(b)); return r; }
; DEV void phase_norm(const float* x, const float* __restrict__ g, u16* h, float* of32, int rows) {
;     ...
;   for (int r = blockIdx.x * 8 + wid; r < rows; r += gridDim.x * 8) {
;     const float* xr = x + (long)r * 1024;
;     f32x4 v[4]; float ss = 0.f;
; #pragma unroll
;     for (int i = 0; i < 4; ++i) { v[i] = *(const f32x4*)(xr + i * 256 + lane * 4); ss += v[i][0] * v[i][0] + v[i][1] * v[i][1] + v[i][2] * v[i][2] + v[i][3] * v[i][3]; }
;     ss = wave_sum(ss, lane);
;     float rs = rsqrtf(ss * (1.f / 1024.f) + 1e-6f);
; #pragma unroll
;     for (int i = 0; i < 4; ++i) {
;       f32x4 o = v[i] * rs * gv[i];
;       if (of32) *(f32x4*)(of32 + (long)r * 1024 + i * 256 + lane * 4) = o;
;       else { u32x2 w; w.x = pack2h(o[0], o[1]); w.y = pack2h(o[2], o[3]); *(u32x2*)(h + (long)r * 1024 + i * 256 + lane * 4) = w; }
;     }
.LBB0_91:
	v_ashrrev_i32_e32 v19, 31, v18
	v_lshlrev_b64 v[30:31], 12, v[18:19]
	v_lshl_add_u64 v[42:43], v[20:21], 0, v[30:31]
	global_load_dwordx4 v[30:33], v[42:43], off
	global_load_dwordx4 v[34:37], v[42:43], off offset:1024
	global_load_dwordx4 v[52:55], v[42:43], off offset:2048
	global_load_dwordx4 v[56:59], v[42:43], off offset:3072
	s_waitcnt vmcnt(0)
	v_mov_b32_e32 v40, v31
	v_mov_b32_e32 v41, v35
	v_mov_b32_e32 v38, v30
	v_mov_b32_e32 v39, v34
	v_pk_mul_f32 v[40:41], v[40:41], v[40:41]
	s_nop 0
	v_pk_fma_f32 v[38:39], v[38:39], v[38:39], v[40:41]
	v_mov_b32_e32 v40, v32
	v_mov_b32_e32 v41, v36
	v_pk_fma_f32 v[38:39], v[40:41], v[40:41], v[38:39]
	v_mov_b32_e32 v40, v33
	v_mov_b32_e32 v41, v37
	v_pk_fma_f32 v[46:47], v[40:41], v[40:41], v[38:39]
	v_mov_b32_e32 v38, v52
	v_mov_b32_e32 v39, v53
	v_mov_b32_e32 v40, v54
	v_mov_b32_e32 v41, v55
	s_nop 0
	v_mov_b32_e32 v42, v56
	v_mov_b32_e32 v43, v57
	v_mov_b32_e32 v44, v58
	v_mov_b32_e32 v45, v59
	v_add_f32_e32 v4, v46, v47
	v_mov_b32_e32 v50, v39
	v_mov_b32_e32 v51, v43
	v_mov_b32_e32 v48, v38
	v_mov_b32_e32 v49, v42
	v_pk_mul_f32 v[50:51], v[50:51], v[50:51]
	s_nop 0
	v_pk_fma_f32 v[48:49], v[48:49], v[48:49], v[50:51]
	v_mov_b32_e32 v50, v40
	v_mov_b32_e32 v51, v44
	v_pk_fma_f32 v[48:49], v[50:51], v[50:51], v[48:49]
	v_mov_b32_e32 v50, v41
	v_mov_b32_e32 v51, v45
	v_pk_fma_f32 v[48:49], v[50:51], v[50:51], v[48:49]
	s_nop 0
	v_add_f32_e32 v4, v4, v48
	v_add_f32_e32 v4, v4, v49
	ds_bpermute_b32 v46, v24, v4
	s_waitcnt lgkmcnt(0)
	v_add_f32_e32 v4, v4, v46
	ds_bpermute_b32 v46, v25, v4
	s_waitcnt lgkmcnt(0)
	v_add_f32_e32 v4, v4, v46
	ds_bpermute_b32 v46, v26, v4
	s_waitcnt lgkmcnt(0)
	v_add_f32_e32 v4, v4, v46
	ds_bpermute_b32 v46, v27, v4
	s_waitcnt lgkmcnt(0)
	v_add_f32_e32 v4, v4, v46
	ds_bpermute_b32 v46, v28, v4
	s_waitcnt lgkmcnt(0)
	v_add_f32_e32 v4, v4, v46
	ds_bpermute_b32 v46, v29, v4
	s_waitcnt lgkmcnt(0)
	v_add_f32_e32 v4, v4, v46
	v_fmamk_f32 v4, v4, 0x3a800000, v188
	v_cmp_gt_f32_e32 vcc, s53, v4
	v_mul_f32_e32 v46, 0x4b800000, v4
	s_nop 0
	v_cndmask_b32_e32 v4, v4, v46, vcc
	v_rsq_f32_e32 v4, v4
	s_nop 0
	v_mul_f32_e32 v46, 0x45800000, v4
	v_cndmask_b32_e32 v4, v4, v46, vcc
	v_pk_mul_f32 v[30:31], v[30:31], v[4:5] op_sel_hi:[1,0]
	v_lshlrev_b64 v[46:47], 11, v[18:19]
	v_pk_mul_f32 v[32:33], v[32:33], v[4:5] op_sel_hi:[1,0]
	v_pk_mul_f32 v[30:31], v[0:1], v[30:31]
	v_lshl_add_u64 v[46:47], v[22:23], 0, v[46:47]
	v_pk_mul_f32 v[32:33], v[2:3], v[32:33]
	v_cvt_pk_bf16_f32 v30, v30, v31
	v_add_u32_e32 v18, s28, v18
	v_cvt_pk_bf16_f32 v31, v32, v33
	global_store_dwordx2 v[46:47], v[30:31], off
	v_pk_mul_f32 v[30:31], v[34:35], v[4:5] op_sel_hi:[1,0]
	v_pk_mul_f32 v[32:33], v[36:37], v[4:5] op_sel_hi:[1,0]
	v_pk_mul_f32 v[30:31], v[6:7], v[30:31]
	v_pk_mul_f32 v[32:33], v[8:9], v[32:33]
	v_cvt_pk_bf16_f32 v30, v30, v31
	v_cmp_le_i32_e32 vcc, s34, v18
	v_cvt_pk_bf16_f32 v31, v32, v33
	global_store_dwordx2 v[46:47], v[30:31], off offset:512
	v_pk_mul_f32 v[30:31], v[38:39], v[4:5] op_sel_hi:[1,0]
	v_pk_mul_f32 v[32:33], v[40:41], v[4:5] op_sel_hi:[1,0]
	v_pk_mul_f32 v[30:31], v[10:11], v[30:31]
	v_pk_mul_f32 v[32:33], v[12:13], v[32:33]
	v_cvt_pk_bf16_f32 v30, v30, v31
	s_or_b64 s[10:11], vcc, s[10:11]
	v_cvt_pk_bf16_f32 v31, v32, v33
	global_store_dwordx2 v[46:47], v[30:31], off offset:1024
	v_pk_mul_f32 v[30:31], v[42:43], v[4:5] op_sel_hi:[1,0]
	v_pk_mul_f32 v[32:33], v[44:45], v[4:5] op_sel_hi:[1,0]
	v_pk_mul_f32 v[30:31], v[14:15], v[30:31]
	v_pk_mul_f32 v[32:33], v[16:17], v[32:33]
	v_cvt_pk_bf16_f32 v30, v30, v31
	s_nop 0
	v_cvt_pk_bf16_f32 v31, v32, v33
	global_store_dwordx2 v[46:47], v[30:31], off offset:1536
	s_andn2_b64 exec, exec, s[10:11]
	s_cbranch_execnz .LBB0_91

; DEV void phase_postmix(const Params& p, int layer, int rows) {
;     ...
;   for (int t = blockIdx.x * 8 + wid; t < rows; t += gridDim.x * 8) {
;     {
;       const int hh = l >> 3, dc = (l & 7) * 8;
;       float l0 = p.lseA[(long)t * 24 + hh], l1 = p.lseA[(long)t * 24 + 8 + hh], l2 = p.lseA[(long)t * 24 + 16 + hh];
;       float m = fmaxf(l0, fmaxf(l1, l2));
;       float w0 = __expf(l0 - m), w1 = __expf(l1 - m), w2 = __expf(l2 - m);
;       float inv = __builtin_amdgcn_rcpf(w0 + w1 + w2);
;       w0 *= inv; w1 *= inv; w2 *= inv;
;       const long eo = (long)t * 512 + hh * 64 + dc;
;       u16* base = p.oA + eo;
;       u32x4 a = *(const u32x4*)base, b = *(const u32x4*)(p.h + eo), c = *(const u32x4*)(p.h + (long)p.GT * 512 + eo);
;       u32x4 o;
;       o.x = pack2h(w0 * bflo(a.x) + w1 * bflo(b.x) + w2 * bflo(c.x), w0 * bfhi(a.x) + w1 * bfhi(b.x) + w2 * bfhi(c.x));
;       o.y = pack2h(w0 * bflo(a.y) + w1 * bflo(b.y) + w2 * bflo(c.y), w0 * bfhi(a.y) + w1 * bfhi(b.y) + w2 * bfhi(c.y));
;       o.z = pack2h(w0 * bflo(a.z) + w1 * bflo(b.z) + w2 * bflo(c.z), w0 * bfhi(a.z) + w1 * bfhi(b.z) + w2 * bfhi(c.z));
;       o.w = pack2h(w0 * bflo(a.w) + w1 * bflo(b.w) + w2 * bflo(c.w), w0 * bfhi(a.w) + w1 * bfhi(b.w) + w2 * bfhi(c.w));
;       *(u32x4*)base = o;
;     }
;     {
;       const int hh = l >> 4, dv0 = (l & 15) * 16;
;       u16* base = p.oB + (long)t * 2048 + hh * 256 + dv0;
;       const u16* rb = p.proj + (long)t * LDR + C_RB + hh * 256 + dv0;
;       const float* ng = p.gla_norm_g + layer * 256 + dv0;
;       float o[16]; float ss = 0.f;
; #pragma unroll
;       for (int q = 0; q < 2; ++q) {
;         u32x4 f = *(const u32x4*)(base + q * 8), bk = *(const u32x4*)(base + 1024 + q * 8);
;         o[q * 8 + 0] = bflo(f.x) + bflo(bk.x); o[q * 8 + 1] = bfhi(f.x) + bfhi(bk.x);
;         o[q * 8 + 2] = bflo(f.y) + bflo(bk.y); o[q * 8 + 3] = bfhi(f.y) + bfhi(bk.y);
;         o[q * 8 + 4] = bflo(f.z) + bflo(bk.z); o[q * 8 + 5] = bfhi(f.z) + bfhi(bk.z);
;         o[q * 8 + 6] = bflo(f.w) + bflo(bk.w); o[q * 8 + 7] = bfhi(f.w) + bfhi(bk.w);
;       }
; #pragma unroll
;       for (int i = 0; i < 16; ++i) ss += o[i] * o[i];
;       ss += shx(ss, 1, l); ss += shx(ss, 2, l); ss += shx(ss, 4, l); ss += shx(ss, 8, l);
;       float rs = rsqrtf(ss * (1.f / 256.f) + 1e-6f);
; #pragma unroll
;       for (int q = 0; q < 2; ++q) {
.LBB0_99:
	v_ashrrev_i32_e32 v129, 31, v10
	v_mov_b32_e32 v128, v10
	v_lshlrev_b64 v[130:131], 10, v[128:129]
	v_lshl_or_b32 v130, v12, 1, v130
	v_lshl_add_u64 v[132:133], s[78:79], 0, v[130:131]
	global_load_dwordx4 v[60:63], v[132:133], off
	v_lshlrev_b64 v[130:131], 12, v[128:129]
	v_lshl_add_u64 v[132:133], v[14:15], 0, v[130:131]
	global_load_dwordx4 v[64:67], v[132:133], off offset:16
	global_load_dwordx4 v[68:71], v[132:133], off
	global_load_dwordx4 v[72:75], v[132:133], off offset:2064
	global_load_dwordx4 v[76:79], v[132:133], off offset:2048
	v_mov_b64_e32 v[130:131], s[76:77]
	v_mad_i64_i32 v[130:131], vcc, v10, s61, v[130:131]
	v_lshl_add_u64 v[130:131], v[130:131], 0, v[4:5]
	v_mov_b32_e32 v135, v5
	v_mov_b32_e32 v134, v20
	v_lshl_add_u64 v[130:131], v[130:131], 0, v[134:135]
	v_add_co_u32_e32 v130, vcc, 0x1000, v130
	s_nop 1
	v_addc_co_u32_e32 v131, vcc, 0, v131, vcc
	global_load_dwordx4 v[80:83], v[130:131], off
	global_load_dwordx4 v[84:87], v[130:131], off offset:16
	global_load_dwordx4 v[88:91], v[16:17], off offset:16
	global_load_dwordx4 v[92:95], v[16:17], off
	global_load_dwordx4 v[96:99], v[16:17], off offset:48
	global_load_dwordx4 v[100:103], v[16:17], off offset:32
	v_mad_i64_i32 v[0:1], s[10:11], v10, s29, v[18:19]
	global_load_dword v2, v[0:1], off
	global_load_dword v3, v[0:1], off offset:32
	s_nop 0
	global_load_dword v0, v[0:1], off offset:64
	v_ashrrev_i32_e32 v11, 31, v10
	v_lshlrev_b64 v[22:23], 10, v[10:11]
	v_lshl_or_b32 v22, v12, 1, v22
	v_lshl_add_u64 v[6:7], s[72:73], 0, v[22:23]
	v_lshl_add_u64 v[30:31], s[78:79], 0, v[22:23]
	global_load_dwordx4 v[6:9], v[6:7], off
	v_lshl_add_u64 v[22:23], s[36:37], 0, v[22:23]
	global_load_dwordx4 v[22:25], v[22:23], off
	s_waitcnt vmcnt(0)
	v_max3_f32 v1, v2, v3, v0
	v_sub_f32_e32 v2, v2, v1
	v_mul_f32_e32 v2, 0x3fb8aa3b, v2
	v_exp_f32_e32 v27, v2
	v_sub_f32_e32 v2, v3, v1
	v_mul_f32_e32 v2, 0x3fb8aa3b, v2
	v_sub_f32_e32 v0, v0, v1
	v_exp_f32_e32 v2, v2
	v_mul_f32_e32 v0, 0x3fb8aa3b, v0
	v_exp_f32_e32 v26, v0
	v_lshlrev_b32_e32 v29, 16, v6
	v_add_f32_e32 v0, v27, v2
	v_and_b32_e32 v32, 0xffff0000, v6
	v_add_f32_e32 v0, v26, v0
	v_rcp_f32_e32 v28, v0
	v_lshlrev_b32_e32 v33, 16, v7
	v_and_b32_e32 v34, 0xffff0000, v7
	v_lshlrev_b32_e32 v35, 16, v8
	v_mul_f32_e32 v21, v2, v28
	v_mov_b32_e32 v0, v60
	v_mov_b32_e32 v1, v61
	v_mov_b32_e32 v2, v62
	v_mov_b32_e32 v3, v63
	v_pk_mul_f32 v[6:7], v[26:27], v[28:29] op_sel_hi:[1,0]
	v_lshlrev_b32_e32 v26, 16, v22
	v_and_b32_e32 v8, 0xffff0000, v8
	v_lshlrev_b32_e32 v36, 16, v9
	v_lshlrev_b32_e32 v27, 16, v0
	v_pk_mul_f32 v[26:27], v[6:7], v[26:27]
	s_nop 0
	v_fma_f32 v27, v21, v29, v27
	v_add_f32_e32 v28, v26, v27
	v_and_b32_e32 v27, 0xffff0000, v0
	v_and_b32_e32 v26, 0xffff0000, v22
	v_pk_mul_f32 v[26:27], v[6:7], v[26:27]
	s_nop 0
	v_fma_f32 v0, v21, v32, v27
	v_add_f32_e32 v0, v26, v0
	v_lshlrev_b32_e32 v27, 16, v1
	v_lshlrev_b32_e32 v26, 16, v23
	v_pk_mul_f32 v[26:27], v[6:7], v[26:27]
	v_cvt_pk_bf16_f32 v0, v28, v0
	s_nop 0
	v_fma_f32 v22, v21, v33, v27
	v_add_f32_e32 v28, v26, v22
	v_and_b32_e32 v27, 0xffff0000, v1
	v_and_b32_e32 v26, 0xffff0000, v23
	v_pk_mul_f32 v[22:23], v[6:7], v[26:27]
	s_nop 0
	v_fma_f32 v1, v21, v34, v23
	v_add_f32_e32 v1, v22, v1
	v_lshlrev_b32_e32 v23, 16, v2
	v_lshlrev_b32_e32 v22, 16, v24
	v_pk_mul_f32 v[22:23], v[6:7], v[22:23]
	v_cvt_pk_bf16_f32 v1, v28, v1
	s_nop 0
	v_fma_f32 v23, v21, v35, v23
	v_add_f32_e32 v26, v22, v23
	v_and_b32_e32 v23, 0xffff0000, v2
	v_and_b32_e32 v22, 0xffff0000, v24
	v_pk_mul_f32 v[22:23], v[6:7], v[22:23]
	s_nop 0
	v_fma_f32 v2, v21, v8, v23
	v_add_f32_e32 v2, v22, v2
	v_lshlrev_b32_e32 v23, 16, v3
	v_lshlrev_b32_e32 v22, 16, v25
	v_pk_mul_f32 v[22:23], v[6:7], v[22:23]
	v_cvt_pk_bf16_f32 v2, v26, v2
	s_nop 0
	v_fma_f32 v8, v21, v36, v23
	v_add_f32_e32 v22, v22, v8
	v_and_b32_e32 v23, 0xffff0000, v9
	v_and_b32_e32 v9, 0xffff0000, v3
	v_and_b32_e32 v8, 0xffff0000, v25
	v_pk_mul_f32 v[6:7], v[6:7], v[8:9]
	s_nop 0
	v_fma_f32 v3, v21, v23, v7
	v_add_f32_e32 v3, v6, v3
	v_cvt_pk_bf16_f32 v3, v22, v3
	global_store_dwordx4 v[30:31], v[0:3], off
	v_mov_b32_e32 v21, v5
	s_nop 0
	v_lshlrev_b64 v[0:1], 12, v[10:11]
	v_lshl_add_u64 v[22:23], v[14:15], 0, v[0:1]
	v_mov_b64_e32 v[0:1], s[76:77]
	v_mad_i64_i32 v[0:1], s[10:11], v10, s61, v[0:1]
	v_lshl_add_u64 v[6:7], v[0:1], 0, v[4:5]
	v_mov_b32_e32 v0, v64
	v_mov_b32_e32 v1, v65
	v_mov_b32_e32 v2, v66
	v_mov_b32_e32 v3, v67
	v_mov_b32_e32 v24, v68
	v_mov_b32_e32 v25, v69
	v_mov_b32_e32 v26, v70
	v_mov_b32_e32 v27, v71
	v_mov_b32_e32 v50, v72
	v_mov_b32_e32 v51, v73
	v_mov_b32_e32 v52, v74
	v_mov_b32_e32 v53, v75
	v_mov_b32_e32 v28, v76
	v_mov_b32_e32 v29, v77
	v_mov_b32_e32 v30, v78
	v_mov_b32_e32 v31, v79
	v_lshl_add_u64 v[6:7], v[6:7], 0, v[20:21]
	s_mov_b64 s[10:11], 0x1000
	v_add_u32_e32 v10, s28, v10
	v_lshlrev_b32_e32 v8, 16, v24
	v_lshlrev_b32_e32 v9, 16, v28
	v_add_f32_e32 v49, v9, v8
	v_and_b32_e32 v8, 0xffff0000, v28
	v_and_b32_e32 v9, 0xffff0000, v24
	v_add_f32_e32 v48, v8, v9
	v_lshlrev_b32_e32 v8, 16, v25
	v_lshlrev_b32_e32 v9, 16, v29
	v_add_f32_e32 v43, v9, v8
	v_and_b32_e32 v8, 0xffff0000, v29
	v_and_b32_e32 v9, 0xffff0000, v25
	v_mul_f32_e32 v21, v49, v49
	v_add_f32_e32 v41, v8, v9
	v_lshlrev_b32_e32 v8, 16, v26
	v_lshlrev_b32_e32 v9, 16, v30
	v_fmac_f32_e32 v21, v48, v48
	v_add_f32_e32 v39, v9, v8
	v_and_b32_e32 v8, 0xffff0000, v30
	v_and_b32_e32 v9, 0xffff0000, v26
	v_fmac_f32_e32 v21, v43, v43
	v_add_f32_e32 v37, v8, v9
	v_lshlrev_b32_e32 v8, 16, v27
	v_lshlrev_b32_e32 v9, 16, v31
	v_fmac_f32_e32 v21, v41, v41
	v_add_f32_e32 v35, v9, v8
	v_and_b32_e32 v8, 0xffff0000, v31
	v_and_b32_e32 v9, 0xffff0000, v27
	v_fmac_f32_e32 v21, v39, v39
	v_add_f32_e32 v33, v8, v9
	v_lshlrev_b32_e32 v8, 16, v0
	v_lshlrev_b32_e32 v9, 16, v50
	v_fmac_f32_e32 v21, v37, v37
	v_add_f32_e32 v47, v9, v8
	v_and_b32_e32 v8, 0xffff0000, v50
	v_and_b32_e32 v0, 0xffff0000, v0
	v_fmac_f32_e32 v21, v35, v35
	v_add_f32_e32 v11, v8, v0
	v_lshlrev_b32_e32 v9, 16, v51
	v_lshlrev_b32_e32 v25, 16, v1
	v_and_b32_e32 v8, 0xffff0000, v51
	v_and_b32_e32 v24, 0xffff0000, v1
	v_fmac_f32_e32 v21, v33, v33
	v_pk_add_f32 v[28:29], v[24:25], v[8:9]
	v_fmac_f32_e32 v21, v47, v47
	v_lshlrev_b32_e32 v1, 16, v52
	v_lshlrev_b32_e32 v27, 16, v2
	v_and_b32_e32 v0, 0xffff0000, v52
	v_and_b32_e32 v26, 0xffff0000, v2
	v_pk_mul_f32 v[8:9], v[28:29], v[28:29]
	v_fmac_f32_e32 v21, v11, v11
	v_pk_add_f32 v[26:27], v[26:27], v[0:1]
	v_add_f32_e32 v9, v9, v21
	v_pk_mul_f32 v[0:1], v[26:27], v[26:27]
	v_and_b32_e32 v2, 0xffff0000, v3
	v_lshlrev_b32_e32 v3, 16, v3
	v_and_b32_e32 v24, 0xffff0000, v53
	v_lshlrev_b32_e32 v25, 16, v53
	v_add_f32_e32 v8, v8, v9
	v_pk_add_f32 v[24:25], v[2:3], v[24:25]
	v_add_f32_e32 v1, v1, v8
	v_pk_mul_f32 v[2:3], v[24:25], v[24:25]
	v_add_f32_e32 v0, v0, v1
	v_add_f32_e32 v0, v3, v0
	v_add_f32_e32 v0, v2, v0
	ds_bpermute_b32 v1, v13, v0
	v_lshl_add_u64 v[30:31], v[6:7], 0, s[10:11]
	s_movk_i32 s10, 0x1000
	s_waitcnt lgkmcnt(0)
; DEV unsigned pack2h(float a, float b) { unsigned r; asm("v_cvt_pk_bf16_f32 %0, %1, %2" : "=v"(r) : "v"(a), "v"(b)); return r; }
; DEV float shx(float v, int m, int lane) { return __int_as_float(__builtin_amdgcn_ds_bpermute((lane ^ m) << 2, __float_as_int(v))); }
; DEV float bflo(unsigned u) { return __uint_as_float(u << 16); }
; DEV float bfhi(unsigned u) { return __uint_as_float(u & 0xffff0000u); }
; DEV float sigm(float x) { return __builtin_amdgcn_rcpf(1.f + __expf(-x)); }
; DEV void phase_postmix(const Params& p, int layer, int rows) {
;     ...
;     {
;       const int hh = l >> 4, dv0 = (l & 15) * 16;
;       u16* base = p.oB + (long)t * 2048 + hh * 256 + dv0;
;       const u16* rb = p.proj + (long)t * LDR + C_RB + hh * 256 + dv0;
;       const float* ng = p.gla_norm_g + layer * 256 + dv0;
;       float o[16]; float ss = 0.f;
; #pragma unroll
;       for (int q = 0; q < 2; ++q) {
;         u32x4 f = *(const u32x4*)(base + q * 8), bk = *(const u32x4*)(base + 1024 + q * 8);
;         o[q * 8 + 0] = bflo(f.x) + bflo(bk.x); o[q * 8 + 1] = bfhi(f.x) + bfhi(bk.x);
;         o[q * 8 + 2] = bflo(f.y) + bflo(bk.y); o[q * 8 + 3] = bfhi(f.y) + bfhi(bk.y);
;         o[q * 8 + 4] = bflo(f.z) + bflo(bk.z); o[q * 8 + 5] = bfhi(f.z) + bfhi(bk.z);
;         o[q * 8 + 6] = bflo(f.w) + bflo(bk.w); o[q * 8 + 7] = bfhi(f.w) + bfhi(bk.w);
;       }
; #pragma unroll
;       for (int i = 0; i < 16; ++i) ss += o[i] * o[i];
;       ss += shx(ss, 1, l); ss += shx(ss, 2, l); ss += shx(ss, 4, l); ss += shx(ss, 8, l);
;       float rs = rsqrtf(ss * (1.f / 256.f) + 1e-6f);
; #pragma unroll
;       for (int q = 0; q < 2; ++q) {
;         u32x4 rr = *(const u32x4*)(rb + q * 8);
;         float rv[8] = {bflo(rr.x), bfhi(rr.x), bflo(rr.y), bfhi(rr.y), bflo(rr.z), bfhi(rr.z), bflo(rr.w), bfhi(rr.w)};
;         float ov[8];
; #pragma unroll
;         for (int i = 0; i < 8; ++i) { float r_ = rv[i]; ov[i] = o[q * 8 + i] * rs * ng[q * 8 + i] * (r_ * sigm(r_)); }
;         u32x4 w_; w_.x = pack2h(ov[0], ov[1]); w_.y = pack2h(ov[2], ov[3]); w_.z = pack2h(ov[4], ov[5]); w_.w = pack2h(ov[6], ov[7]);
;         *(u32x4*)(base + q * 8) = w_;
;       }
	v_add_f32_e32 v0, v0, v1
	ds_bpermute_b32 v1, v44, v0
	s_waitcnt lgkmcnt(0)
	v_add_f32_e32 v0, v0, v1
	ds_bpermute_b32 v1, v45, v0
	s_waitcnt lgkmcnt(0)
	v_add_f32_e32 v0, v0, v1
	ds_bpermute_b32 v1, v46, v0
	s_waitcnt lgkmcnt(0)
	v_add_f32_e32 v0, v0, v1
	v_fmamk_f32 v0, v0, 0x3b800000, v188
	v_cmp_gt_f32_e32 vcc, s53, v0
	v_mul_f32_e32 v1, 0x4b800000, v0
	s_nop 0
	v_cndmask_b32_e32 v0, v0, v1, vcc
	v_rsq_f32_e32 v0, v0
	s_nop 0
	v_mul_f32_e32 v1, 0x45800000, v0
	v_cndmask_b32_e32 v21, v0, v1, vcc
	v_add_co_u32_e32 v0, vcc, s10, v6
	v_mul_f32_e32 v51, v49, v21
	s_nop 0
	v_addc_co_u32_e32 v1, vcc, 0, v7, vcc
	v_mov_b32_e32 v0, v80
	v_mov_b32_e32 v1, v81
	v_mov_b32_e32 v2, v82
	v_mov_b32_e32 v3, v83
	v_mul_f32_e32 v41, v41, v21
	v_mul_f32_e32 v39, v39, v21
	v_mul_f32_e32 v37, v37, v21
	v_mul_f32_e32 v35, v35, v21
	v_mul_f32_e32 v53, v48, v21
	v_mul_f32_e32 v33, v33, v21
	v_mul_f32_e32 v43, v43, v21
	v_cmp_le_i32_e32 vcc, s34, v10
	s_or_b64 s[8:9], vcc, s[8:9]
	v_lshlrev_b32_e32 v50, 16, v0
	v_and_b32_e32 v52, 0xffff0000, v0
	v_lshlrev_b32_e32 v42, 16, v1
	v_and_b32_e32 v40, 0xffff0000, v1
	v_lshlrev_b32_e32 v38, 16, v2
	v_and_b32_e32 v36, 0xffff0000, v2
	v_lshlrev_b32_e32 v34, 16, v3
	v_and_b32_e32 v32, 0xffff0000, v3
	v_mov_b32_e32 v0, v88
	v_mov_b32_e32 v1, v89
	v_mov_b32_e32 v2, v90
	v_mov_b32_e32 v3, v91
	v_mov_b32_e32 v6, v92
	v_mov_b32_e32 v7, v93
	v_mov_b32_e32 v8, v94
	v_mov_b32_e32 v9, v95
	v_mul_f32_e32 v49, 0xbfb8aa3b, v50
	v_exp_f32_e32 v49, v49
	v_mov_b32_e32 v55, v6
	v_add_f32_e32 v49, 1.0, v49
	v_rcp_f32_e32 v54, v49
	v_mul_f32_e32 v6, 0xbfb8aa3b, v52
	v_exp_f32_e32 v6, v6
	v_pk_mul_f32 v[50:51], v[54:55], v[50:51]
	s_nop 0
	v_mul_f32_e32 v49, v50, v51
	v_mov_b32_e32 v51, v8
	v_mul_f32_e32 v8, 0xbfb8aa3b, v40
	v_exp_f32_e32 v8, v8
	v_add_f32_e32 v6, 1.0, v6
	v_rcp_f32_e32 v6, v6
	v_add_f32_e32 v8, 1.0, v8
	v_rcp_f32_e32 v8, v8
	v_pk_mul_f32 v[6:7], v[6:7], v[52:53]
	v_pk_mul_f32 v[8:9], v[8:9], v[40:41]
	s_nop 0
	v_mul_f32_e32 v40, v8, v9
	v_mul_f32_e32 v8, 0xbfb8aa3b, v38
	v_mov_b32_e32 v9, v0
	v_mul_f32_e32 v0, 0xbfb8aa3b, v36
	v_exp_f32_e32 v8, v8
	v_exp_f32_e32 v0, v0
	v_mul_f32_e32 v6, v6, v7
	v_mul_f32_e32 v7, 0xbfb8aa3b, v42
	v_add_f32_e32 v8, 1.0, v8
	v_add_f32_e32 v0, 1.0, v0
	v_rcp_f32_e32 v8, v8
	v_rcp_f32_e32 v0, v0
	v_exp_f32_e32 v7, v7
	v_mul_f32_e32 v41, v26, v21
	v_pk_mul_f32 v[8:9], v[8:9], v[38:39]
	v_pk_mul_f32 v[0:1], v[0:1], v[36:37]
	v_mul_f32_e32 v8, v8, v9
	v_mul_f32_e32 v9, v0, v1
	v_mul_f32_e32 v0, 0xbfb8aa3b, v34
	v_exp_f32_e32 v0, v0
	v_mov_b32_e32 v1, v2
	v_add_f32_e32 v7, 1.0, v7
	v_rcp_f32_e32 v50, v7
	v_add_f32_e32 v0, 1.0, v0
	v_rcp_f32_e32 v0, v0
	v_mul_f32_e32 v37, v28, v21
	v_pk_mul_f32 v[42:43], v[50:51], v[42:43]
	v_mul_f32_e32 v39, v27, v21
	v_pk_mul_f32 v[0:1], v[0:1], v[34:35]
	v_mul_f32_e32 v7, v42, v43
	v_mul_f32_e32 v34, v0, v1
	v_mul_f32_e32 v0, 0xbfb8aa3b, v32
	v_exp_f32_e32 v0, v0
	v_mul_f32_e32 v35, v29, v21
	v_mul_f32_e32 v43, v25, v21
	v_add_f32_e32 v0, 1.0, v0
	v_rcp_f32_e32 v2, v0
	s_nop 0
	v_pk_mul_f32 v[0:1], v[2:3], v[32:33]
	s_nop 0
	v_mul_f32_e32 v3, v0, v1
	v_cvt_pk_bf16_f32 v0, v49, v6
	v_cvt_pk_bf16_f32 v1, v7, v40
	v_cvt_pk_bf16_f32 v2, v8, v9
	v_cvt_pk_bf16_f32 v3, v34, v3
	global_store_dwordx4 v[22:23], v[0:3], off
	s_nop 1
	v_mov_b32_e32 v0, v84
	v_mov_b32_e32 v1, v85
	v_mov_b32_e32 v2, v86
	v_mov_b32_e32 v3, v87
	v_mul_f32_e32 v49, v24, v21
	v_mul_f32_e32 v31, v47, v21
	v_lshlrev_b32_e32 v30, 16, v0
	v_and_b32_e32 v32, 0xffff0000, v0
	v_lshlrev_b32_e32 v34, 16, v1
	v_and_b32_e32 v36, 0xffff0000, v1
	v_lshlrev_b32_e32 v38, 16, v2
	v_and_b32_e32 v40, 0xffff0000, v2
	v_lshlrev_b32_e32 v42, 16, v3
	v_and_b32_e32 v48, 0xffff0000, v3
	v_mov_b32_e32 v0, v96
	v_mov_b32_e32 v1, v97
	v_mov_b32_e32 v2, v98
	v_mov_b32_e32 v3, v99
	v_mov_b32_e32 v6, v100
	v_mov_b32_e32 v7, v101
	v_mov_b32_e32 v8, v102
	v_mov_b32_e32 v9, v103
	v_mul_f32_e32 v33, 0xbfb8aa3b, v30
	v_exp_f32_e32 v33, v33
	v_mov_b32_e32 v51, v6
	v_mul_f32_e32 v6, 0xbfb8aa3b, v32
	v_exp_f32_e32 v6, v6
	v_add_f32_e32 v33, 1.0, v33
	v_rcp_f32_e32 v50, v33
	v_mul_f32_e32 v33, v11, v21
	v_add_f32_e32 v6, 1.0, v6
	v_rcp_f32_e32 v6, v6
	v_pk_mul_f32 v[30:31], v[50:51], v[30:31]
	v_pk_mul_f32 v[6:7], v[6:7], v[32:33]
	s_nop 0
	v_mul_f32_e32 v11, v6, v7
	v_mul_f32_e32 v6, 0xbfb8aa3b, v34
	v_exp_f32_e32 v6, v6
	v_mov_b32_e32 v7, v8
	v_mul_f32_e32 v30, v30, v31
	v_add_f32_e32 v6, 1.0, v6
	v_rcp_f32_e32 v6, v6
	s_nop 0
	v_pk_mul_f32 v[6:7], v[6:7], v[34:35]
	s_nop 0
	v_mul_f32_e32 v29, v6, v7
	v_mul_f32_e32 v6, 0xbfb8aa3b, v36
	v_exp_f32_e32 v6, v6
	s_nop 0
	v_add_f32_e32 v6, 1.0, v6
	v_rcp_f32_e32 v8, v6
	s_nop 0
	v_pk_mul_f32 v[6:7], v[8:9], v[36:37]
	s_nop 0
	v_mul_f32_e32 v8, v6, v7
	v_mul_f32_e32 v6, 0xbfb8aa3b, v38
	v_mov_b32_e32 v7, v0
	v_mul_f32_e32 v0, 0xbfb8aa3b, v40
	v_exp_f32_e32 v6, v6
	v_exp_f32_e32 v0, v0
	v_add_f32_e32 v6, 1.0, v6
	v_add_f32_e32 v0, 1.0, v0
	v_rcp_f32_e32 v6, v6
	v_rcp_f32_e32 v0, v0
	v_pk_mul_f32 v[6:7], v[6:7], v[38:39]
	v_pk_mul_f32 v[0:1], v[0:1], v[40:41]
	v_mul_f32_e32 v6, v6, v7
	v_mul_f32_e32 v7, v0, v1
	v_mul_f32_e32 v0, 0xbfb8aa3b, v42
	v_exp_f32_e32 v0, v0
	v_mov_b32_e32 v1, v2
	v_add_f32_e32 v0, 1.0, v0
	v_rcp_f32_e32 v0, v0
	s_nop 0
	v_pk_mul_f32 v[0:1], v[0:1], v[42:43]
	s_nop 0
	v_mul_f32_e32 v9, v0, v1
	v_mul_f32_e32 v0, 0xbfb8aa3b, v48
	v_exp_f32_e32 v0, v0
	s_nop 0
	v_add_f32_e32 v0, 1.0, v0
	v_rcp_f32_e32 v2, v0
	s_nop 0
	v_pk_mul_f32 v[0:1], v[2:3], v[48:49]
	s_nop 0
	v_mul_f32_e32 v3, v0, v1
	v_cvt_pk_bf16_f32 v0, v30, v11
	v_cvt_pk_bf16_f32 v1, v29, v8
	v_cvt_pk_bf16_f32 v2, v6, v7
	v_cvt_pk_bf16_f32 v3, v9, v3
	global_store_dwordx4 v[22:23], v[0:3], off offset:16
	s_andn2_b64 exec, exec, s[8:9]
	s_cbranch_execnz .LBB0_99

; DEV unsigned pack2h(float a, float b) { unsigned r; asm("v_cvt_pk_bf16_f32 %0, %1, %2" : "=v"(r) : "v"(a), "v"(b)); return r; }
; DEV void phase_norm(const float* x, const float* __restrict__ g, u16* h, float* of32, int rows) {
;     ...
;   for (int r = blockIdx.x * 8 + wid; r < rows; r += gridDim.x * 8) {
;     const float* xr = x + (long)r * 1024;
;     f32x4 v[4]; float ss = 0.f;
; #pragma unroll
;     for (int i = 0; i < 4; ++i) { v[i] = *(const f32x4*)(xr + i * 256 + lane * 4); ss += v[i][0] * v[i][0] + v[i][1] * v[i][1] + v[i][2] * v[i][2] + v[i][3] * v[i][3]; }
;     ss = wave_sum(ss, lane);
;     float rs = rsqrtf(ss * (1.f / 1024.f) + 1e-6f);
; #pragma unroll
;     for (int i = 0; i < 4; ++i) {
;       f32x4 o = v[i] * rs * gv[i];
;       if (of32) *(f32x4*)(of32 + (long)r * 1024 + i * 256 + lane * 4) = o;
;       else { u32x2 w; w.x = pack2h(o[0], o[1]); w.y = pack2h(o[2], o[3]); *(u32x2*)(h + (long)r * 1024 + i * 256 + lane * 4) = w; }
;     }
.LBB0_175:
	v_ashrrev_i32_e32 v19, 31, v18
	v_lshlrev_b64 v[30:31], 12, v[18:19]
	v_lshl_add_u64 v[42:43], v[20:21], 0, v[30:31]
	global_load_dwordx4 v[30:33], v[42:43], off
	global_load_dwordx4 v[34:37], v[42:43], off offset:1024
	global_load_dwordx4 v[52:55], v[42:43], off offset:2048
	global_load_dwordx4 v[56:59], v[42:43], off offset:3072
	s_waitcnt vmcnt(0)
	v_mov_b32_e32 v40, v31
	v_mov_b32_e32 v41, v35
	v_mov_b32_e32 v38, v30
	v_mov_b32_e32 v39, v34
	v_pk_mul_f32 v[40:41], v[40:41], v[40:41]
	s_nop 0
	v_pk_fma_f32 v[38:39], v[38:39], v[38:39], v[40:41]
	v_mov_b32_e32 v40, v32
	v_mov_b32_e32 v41, v36
	v_pk_fma_f32 v[38:39], v[40:41], v[40:41], v[38:39]
	v_mov_b32_e32 v40, v33
	v_mov_b32_e32 v41, v37
	v_pk_fma_f32 v[46:47], v[40:41], v[40:41], v[38:39]
	v_mov_b32_e32 v38, v52
	v_mov_b32_e32 v39, v53
	v_mov_b32_e32 v40, v54
	v_mov_b32_e32 v41, v55
	s_nop 0
	v_mov_b32_e32 v42, v56
	v_mov_b32_e32 v43, v57
	v_mov_b32_e32 v44, v58
	v_mov_b32_e32 v45, v59
	v_add_f32_e32 v4, v46, v47
	v_mov_b32_e32 v50, v39
	v_mov_b32_e32 v51, v43
	v_mov_b32_e32 v48, v38
	v_mov_b32_e32 v49, v42
	v_pk_mul_f32 v[50:51], v[50:51], v[50:51]
	s_nop 0
	v_pk_fma_f32 v[48:49], v[48:49], v[48:49], v[50:51]
	v_mov_b32_e32 v50, v40
	v_mov_b32_e32 v51, v44
	v_pk_fma_f32 v[48:49], v[50:51], v[50:51], v[48:49]
	v_mov_b32_e32 v50, v41
	v_mov_b32_e32 v51, v45
	v_pk_fma_f32 v[48:49], v[50:51], v[50:51], v[48:49]
	s_nop 0
	v_add_f32_e32 v4, v4, v48
	v_add_f32_e32 v4, v4, v49
	ds_bpermute_b32 v46, v24, v4
	s_waitcnt lgkmcnt(0)
	v_add_f32_e32 v4, v4, v46
	ds_bpermute_b32 v46, v25, v4
	s_waitcnt lgkmcnt(0)
	v_add_f32_e32 v4, v4, v46
	ds_bpermute_b32 v46, v26, v4
	s_waitcnt lgkmcnt(0)
	v_add_f32_e32 v4, v4, v46
	ds_bpermute_b32 v46, v27, v4
	s_waitcnt lgkmcnt(0)
	v_add_f32_e32 v4, v4, v46
	ds_bpermute_b32 v46, v28, v4
	s_waitcnt lgkmcnt(0)
	v_add_f32_e32 v4, v4, v46
	ds_bpermute_b32 v46, v29, v4
	s_waitcnt lgkmcnt(0)
	v_add_f32_e32 v4, v4, v46
	v_fmamk_f32 v4, v4, 0x3a800000, v188
	v_cmp_gt_f32_e32 vcc, s53, v4
	v_mul_f32_e32 v46, 0x4b800000, v4
	s_nop 0
	v_cndmask_b32_e32 v4, v4, v46, vcc
	v_rsq_f32_e32 v4, v4
	s_nop 0
	v_mul_f32_e32 v46, 0x45800000, v4
	v_cndmask_b32_e32 v4, v4, v46, vcc
	v_pk_mul_f32 v[30:31], v[30:31], v[4:5] op_sel_hi:[1,0]
	v_lshlrev_b64 v[46:47], 11, v[18:19]
	v_pk_mul_f32 v[32:33], v[32:33], v[4:5] op_sel_hi:[1,0]
	v_pk_mul_f32 v[30:31], v[0:1], v[30:31]
	v_lshl_add_u64 v[46:47], v[22:23], 0, v[46:47]
	v_pk_mul_f32 v[32:33], v[2:3], v[32:33]
	v_cvt_pk_bf16_f32 v30, v30, v31
	v_add_u32_e32 v18, s10, v18
	v_cvt_pk_bf16_f32 v31, v32, v33
	global_store_dwordx2 v[46:47], v[30:31], off
	v_pk_mul_f32 v[30:31], v[34:35], v[4:5] op_sel_hi:[1,0]
	v_pk_mul_f32 v[32:33], v[36:37], v[4:5] op_sel_hi:[1,0]
	v_pk_mul_f32 v[30:31], v[6:7], v[30:31]
	v_pk_mul_f32 v[32:33], v[8:9], v[32:33]
	v_cvt_pk_bf16_f32 v30, v30, v31
	v_cmp_le_i32_e32 vcc, s34, v18
	v_cvt_pk_bf16_f32 v31, v32, v33
	global_store_dwordx2 v[46:47], v[30:31], off offset:512
	v_pk_mul_f32 v[30:31], v[38:39], v[4:5] op_sel_hi:[1,0]
	v_pk_mul_f32 v[32:33], v[40:41], v[4:5] op_sel_hi:[1,0]
	v_pk_mul_f32 v[30:31], v[10:11], v[30:31]
	v_pk_mul_f32 v[32:33], v[12:13], v[32:33]
	v_cvt_pk_bf16_f32 v30, v30, v31
	s_or_b64 s[8:9], vcc, s[8:9]
	v_cvt_pk_bf16_f32 v31, v32, v33
	global_store_dwordx2 v[46:47], v[30:31], off offset:1024
	v_pk_mul_f32 v[30:31], v[42:43], v[4:5] op_sel_hi:[1,0]
	v_pk_mul_f32 v[32:33], v[44:45], v[4:5] op_sel_hi:[1,0]
	v_pk_mul_f32 v[30:31], v[14:15], v[30:31]
	v_pk_mul_f32 v[32:33], v[16:17], v[32:33]
	v_cvt_pk_bf16_f32 v30, v30, v31
	s_nop 0
	v_cvt_pk_bf16_f32 v31, v32, v33
	global_store_dwordx2 v[46:47], v[30:31], off offset:1536
	s_andn2_b64 exec, exec, s[8:9]
	s_cbranch_execnz .LBB0_175
